# hy_conv input staging rewritten by hand: all loads of a pass issued together, scalar weights, same f32 op order
# speedup vs baseline: 1.1068x; 1.0028x over previous
.LBB0_677:
	s_add_i32 s2, s12, 0xfffffc00
	s_cmpk_gt_i32 s12, 0x3ff
	s_cselect_b64 s[36:37], -1, 0
	s_and_b64 s[0:1], s[36:37], exec
	s_cselect_b32 s2, s2, s12
	s_movk_i32 s0, 0x800
	v_readlane_b32 s40, v253, 2
	s_cselect_b32 s4, 0x100, s0
	s_cselect_b32 s5, 0, 0x2000
	s_cselect_b32 s7, 2, 1
	s_ashr_i32 s3, s2, 31
	s_mul_i32 s6, s2, 0x6000
	v_readlane_b32 s44, v253, 6
	v_readlane_b32 s45, v253, 7
	s_add_i32 s13, s4, -1
	s_add_i32 s10, s2, 0x400
	s_add_i32 s11, s6, 0x1800000
	s_add_i32 s15, s2, 0x800
	s_add_i32 s16, s6, 0x3000000
	s_lshl_b64 s[0:1], s[2:3], 2
	s_mov_b64 s[20:21], s[44:45]
	v_readlane_b32 s42, v253, 4
	v_readlane_b32 s43, v253, 5
	s_add_u32 s8, s20, s0
	s_mov_b64 s[18:19], s[42:43]
	s_addc_u32 s9, s21, s1
	s_add_u32 s0, s18, s0
	s_addc_u32 s1, s19, s1
	v_mov_b32_e32 v0, 0x8000
	s_barrier
	v_readlane_b32 s3, v254, 41
	s_nop 3
	s_cmpk_eq_i32 s3, 0x200
	s_cbranch_scc1 .Lcv_stage
	global_load_dword v8, v65, s[8:9]
	global_load_dword v10, v184, s[8:9]
	global_load_dword v12, v182, s[8:9]
	global_load_dword v14, v0, s[0:1]
	global_load_dword v32, v184, s[0:1]
	v_mov_b32_e32 v0, 0x5000
	global_load_dword v34, v0, s[0:1]
	v_mov_b32_e32 v0, 0x7000
	global_load_dword v36, v0, s[0:1]
	global_load_dword v38, v182, s[0:1]
	v_mov_b32_e32 v0, 0x4000
	global_load_dword v40, v0, s[0:1]
	v_mov_b32_e32 v0, 0x6000
	global_load_dword v42, v0, s[0:1]
	global_load_dword v45, v65, s[0:1]
	v_mov_b32_e32 v0, 0x3000
	global_load_dword v44, v0, s[0:1]
	s_lshl_b32 s3, s5, 1
	s_mul_hi_i32 s1, s15, 0x6000
	s_add_u32 s8, s16, s3
	s_addc_u32 s1, s1, 0
	s_add_u32 s8, s90, s8
	s_addc_u32 s9, s91, s1
	s_mul_hi_i32 s0, s10, 0x6000
	s_add_u32 s1, s11, s3
	s_addc_u32 s0, s0, 0
	s_add_u32 s10, s90, s1
	s_addc_u32 s11, s91, s0
	s_mul_hi_i32 s14, s2, 0x6000
	s_add_u32 s0, s6, s3
	s_addc_u32 s1, s14, 0
	s_add_u32 s18, s90, s0
	v_mov_b32_e32 v55, v118
	s_addc_u32 s19, s91, s1
	v_mov_b32_e32 v70, v52
	v_readlane_b32 s41, v253, 3
	v_readlane_b32 s46, v253, 8
	v_readlane_b32 s47, v253, 9
	v_readlane_b32 s48, v253, 10
	v_readlane_b32 s49, v253, 11
	v_readlane_b32 s50, v253, 12
	v_readlane_b32 s51, v253, 13
	v_readlane_b32 s52, v253, 14
	v_readlane_b32 s53, v253, 15
	v_readlane_b32 s54, v253, 16
	v_readlane_b32 s55, v253, 17
	s_waitcnt vmcnt(10)
	v_mov_b32_e32 v11, v10
	v_mov_b32_e32 v9, v8
	s_waitcnt vmcnt(9)
	v_mov_b32_e32 v13, v12
	s_waitcnt vmcnt(8)
	v_mov_b32_e32 v15, v14
	s_waitcnt vmcnt(7)
	v_mov_b32_e32 v33, v32
	s_waitcnt vmcnt(6)
	v_mov_b32_e32 v35, v34
	v_mov_b32_e32 v46, v34
	v_mov_b32_e32 v47, v32
	s_waitcnt vmcnt(5)
	v_mov_b32_e32 v37, v36
	s_waitcnt vmcnt(4)
	v_mov_b32_e32 v39, v38
	s_waitcnt vmcnt(3)
	v_mov_b32_e32 v41, v40
	v_mov_b32_e32 v48, v40
	v_mov_b32_e32 v49, v38
	s_waitcnt vmcnt(2)
	v_mov_b32_e32 v43, v42
	s_waitcnt vmcnt(1)
	v_mov_b32_e32 v50, v45
	v_mov_b32_e32 v51, v45
	s_waitcnt vmcnt(0)
	v_mov_b32_e32 v60, v44
	v_mov_b32_e32 v61, v44
	s_branch .LBB0_679
.Lcv_stage:
	s_load_dword s40, s[0:1], 0x0
	s_load_dword s41, s[0:1], 0x1000
	s_load_dword s42, s[0:1], 0x2000
	s_load_dword s43, s[0:1], 0x3000
	s_load_dword s44, s[0:1], 0x4000
	s_load_dword s45, s[0:1], 0x5000
	s_load_dword s46, s[0:1], 0x6000
	s_load_dword s47, s[0:1], 0x7000
	s_load_dword s48, s[0:1], 0x8000
	s_load_dword s49, s[8:9], 0x0
	s_load_dword s50, s[8:9], 0x1000
	s_load_dword s51, s[8:9], 0x2000
	s_lshl_b32 s3, s5, 1
	s_mov_b32 s10, s2
	s_mul_hi_u32 s11, s10, 0x6000
	s_mul_i32 s10, s10, 0x6000
	s_add_u32 s10, s10, s3
	s_addc_u32 s11, s11, 0
	s_add_u32 s16, s90, s10
	s_addc_u32 s17, s91, s11
	s_add_i32 s10, s2, 0x400
	s_mul_hi_u32 s11, s10, 0x6000
	s_mul_i32 s10, s10, 0x6000
	s_add_u32 s10, s10, s3
	s_addc_u32 s11, s11, 0
	s_add_u32 s18, s90, s10
	s_addc_u32 s19, s91, s11
	s_add_i32 s10, s2, 0x800
	s_mul_hi_u32 s11, s10, 0x6000
	s_mul_i32 s10, s10, 0x6000
	s_add_u32 s10, s10, s3
	s_addc_u32 s11, s11, 0
	s_add_u32 s20, s90, s10
	s_addc_u32 s21, s91, s11
	v_lshlrev_b32_e32 v60, 5, v176
	v_mov_b32_e32 v63, v60
	v_lshrrev_b32_e32 v46, 1, v176
	v_mul_u32_u24_e32 v55, 80, v46
	v_and_b32_e32 v46, 1, v176
	v_lshl_add_u32 v55, v46, 5, v55
	v_lshlrev_b32_e32 v46, 4, v176
	v_and_b32_e32 v47, s13, v46
	v_cmp_ne_u32_e64 s[52:53], 0, v47
	v_add_u32_e32 v47, 16, v46
	v_and_b32_e32 v47, s13, v47
	v_cmp_ne_u32_e64 s[54:55], 0, v47
	v_add_u32_e32 v47, -2, v60
	v_cndmask_b32_e64 v61, v60, v47, s[52:53]
	v_add_u32_e32 v47, 32, v60
	v_cndmask_b32_e64 v62, v60, v47, s[54:55]
	global_load_dwordx4 v[0:3], v60, s[16:17] nt
	global_load_dwordx4 v[4:7], v60, s[16:17] offset:16 nt
	global_load_ushort v40, v61, s[16:17]
	global_load_ushort v43, v62, s[16:17]
	global_load_dwordx4 v[8:11], v60, s[18:19] nt
	global_load_dwordx4 v[12:15], v60, s[18:19] offset:16 nt
	global_load_ushort v41, v61, s[18:19]
	global_load_ushort v44, v62, s[18:19]
	global_load_dwordx4 v[32:35], v60, s[20:21] nt
	global_load_dwordx4 v[36:39], v60, s[20:21] offset:16 nt
	global_load_ushort v42, v61, s[20:21]
	global_load_ushort v45, v62, s[20:21]
	s_waitcnt lgkmcnt(0)
	s_cmp_lg_u64 s[36:37], 0
	s_cbranch_scc0 .Lcv_stage_1p
	s_waitcnt vmcnt(8)
	v_lshlrev_b32_e32 v236, 16, v0
	v_and_b32_e32 v237, 0xffff0000, v0
	v_lshlrev_b32_e32 v238, 16, v1
	v_and_b32_e32 v239, 0xffff0000, v1
	v_lshlrev_b32_e32 v240, 16, v2
	v_and_b32_e32 v241, 0xffff0000, v2
	v_lshlrev_b32_e32 v242, 16, v3
	v_and_b32_e32 v243, 0xffff0000, v3
	v_lshlrev_b32_e32 v244, 16, v4
	v_and_b32_e32 v245, 0xffff0000, v4
	v_lshlrev_b32_e32 v246, 16, v5
	v_and_b32_e32 v247, 0xffff0000, v5
	v_lshlrev_b32_e32 v248, 16, v6
	v_and_b32_e32 v249, 0xffff0000, v6
	v_lshlrev_b32_e32 v250, 16, v7
	v_and_b32_e32 v251, 0xffff0000, v7
	v_lshlrev_b32_e32 v140, 16, v40
	v_lshlrev_b32_e32 v141, 16, v43
	v_cndmask_b32_e64 v122, 0, v140, s[52:53]
	v_cndmask_b32_e64 v139, 0, v141, s[54:55]
	v_mov_b32_e32 v123, v236
	v_mov_b32_e32 v138, v251
	v_pk_mov_b32 v[124:125], v[236:237], v[238:239] op_sel:[1,0]
	v_pk_mov_b32 v[126:127], v[238:239], v[240:241] op_sel:[1,0]
	v_pk_mov_b32 v[128:129], v[240:241], v[242:243] op_sel:[1,0]
	v_pk_mov_b32 v[130:131], v[242:243], v[244:245] op_sel:[1,0]
	v_pk_mov_b32 v[132:133], v[244:245], v[246:247] op_sel:[1,0]
	v_pk_mov_b32 v[134:135], v[246:247], v[248:249] op_sel:[1,0]
	v_pk_mov_b32 v[136:137], v[248:249], v[250:251] op_sel:[1,0]
	s_add_u32 s16, s16, 0x2000
	s_addc_u32 s17, s17, 0
	global_load_dwordx4 v[0:3], v60, s[16:17] nt
	global_load_dwordx4 v[4:7], v60, s[16:17] offset:16 nt
	global_load_ushort v40, v61, s[16:17]
	global_load_ushort v43, v62, s[16:17]
	v_pk_mul_f32 v[140:141], v[236:237], s[42:43] op_sel:[0,1] op_sel_hi:[1,1]
	v_pk_fma_f32 v[140:141], v[122:123], s[40:41], v[140:141] op_sel:[0,0,0] op_sel_hi:[1,0,1]
	v_pk_fma_f32 v[140:141], v[124:125], s[46:47], v[140:141] op_sel:[0,0,0] op_sel_hi:[1,0,1]
	v_pk_add_f32 v[140:141], s[48:49], v[140:141] op_sel:[1,0] op_sel_hi:[1,1]
	v_cvt_pk_bf16_f32 v66, v140, v141
	v_pk_mul_f32 v[140:141], v[238:239], s[42:43] op_sel:[0,1] op_sel_hi:[1,1]
	v_pk_fma_f32 v[140:141], v[124:125], s[40:41], v[140:141] op_sel:[0,0,0] op_sel_hi:[1,0,1]
	v_pk_fma_f32 v[140:141], v[126:127], s[46:47], v[140:141] op_sel:[0,0,0] op_sel_hi:[1,0,1]
	v_pk_add_f32 v[140:141], s[48:49], v[140:141] op_sel:[1,0] op_sel_hi:[1,1]
	v_cvt_pk_bf16_f32 v67, v140, v141
	v_pk_mul_f32 v[140:141], v[240:241], s[42:43] op_sel:[0,1] op_sel_hi:[1,1]
	v_pk_fma_f32 v[140:141], v[126:127], s[40:41], v[140:141] op_sel:[0,0,0] op_sel_hi:[1,0,1]
	v_pk_fma_f32 v[140:141], v[128:129], s[46:47], v[140:141] op_sel:[0,0,0] op_sel_hi:[1,0,1]
	v_pk_add_f32 v[140:141], s[48:49], v[140:141] op_sel:[1,0] op_sel_hi:[1,1]
	v_cvt_pk_bf16_f32 v68, v140, v141
	v_pk_mul_f32 v[140:141], v[242:243], s[42:43] op_sel:[0,1] op_sel_hi:[1,1]
	v_pk_fma_f32 v[140:141], v[128:129], s[40:41], v[140:141] op_sel:[0,0,0] op_sel_hi:[1,0,1]
	v_pk_fma_f32 v[140:141], v[130:131], s[46:47], v[140:141] op_sel:[0,0,0] op_sel_hi:[1,0,1]
	v_pk_add_f32 v[140:141], s[48:49], v[140:141] op_sel:[1,0] op_sel_hi:[1,1]
	v_cvt_pk_bf16_f32 v69, v140, v141
	v_pk_mul_f32 v[140:141], v[244:245], s[42:43] op_sel:[0,1] op_sel_hi:[1,1]
	v_pk_fma_f32 v[140:141], v[130:131], s[40:41], v[140:141] op_sel:[0,0,0] op_sel_hi:[1,0,1]
	v_pk_fma_f32 v[140:141], v[132:133], s[46:47], v[140:141] op_sel:[0,0,0] op_sel_hi:[1,0,1]
	v_pk_add_f32 v[140:141], s[48:49], v[140:141] op_sel:[1,0] op_sel_hi:[1,1]
	v_cvt_pk_bf16_f32 v70, v140, v141
	v_pk_mul_f32 v[140:141], v[246:247], s[42:43] op_sel:[0,1] op_sel_hi:[1,1]
	v_pk_fma_f32 v[140:141], v[132:133], s[40:41], v[140:141] op_sel:[0,0,0] op_sel_hi:[1,0,1]
	v_pk_fma_f32 v[140:141], v[134:135], s[46:47], v[140:141] op_sel:[0,0,0] op_sel_hi:[1,0,1]
	v_pk_add_f32 v[140:141], s[48:49], v[140:141] op_sel:[1,0] op_sel_hi:[1,1]
	v_cvt_pk_bf16_f32 v71, v140, v141
	v_pk_mul_f32 v[140:141], v[248:249], s[42:43] op_sel:[0,1] op_sel_hi:[1,1]
	v_pk_fma_f32 v[140:141], v[134:135], s[40:41], v[140:141] op_sel:[0,0,0] op_sel_hi:[1,0,1]
	v_pk_fma_f32 v[140:141], v[136:137], s[46:47], v[140:141] op_sel:[0,0,0] op_sel_hi:[1,0,1]
	v_pk_add_f32 v[140:141], s[48:49], v[140:141] op_sel:[1,0] op_sel_hi:[1,1]
	v_cvt_pk_bf16_f32 v72, v140, v141
	v_pk_mul_f32 v[140:141], v[250:251], s[42:43] op_sel:[0,1] op_sel_hi:[1,1]
	v_pk_fma_f32 v[140:141], v[136:137], s[40:41], v[140:141] op_sel:[0,0,0] op_sel_hi:[1,0,1]
	v_pk_fma_f32 v[140:141], v[138:139], s[46:47], v[140:141] op_sel:[0,0,0] op_sel_hi:[1,0,1]
	v_pk_add_f32 v[140:141], s[48:49], v[140:141] op_sel:[1,0] op_sel_hi:[1,1]
	v_cvt_pk_bf16_f32 v73, v140, v141
	ds_write_b128 v63, v[66:69] offset:20480
	ds_write_b128 v63, v[70:73] offset:20496
	s_waitcnt vmcnt(8)
	v_lshlrev_b32_e32 v236, 16, v8
	v_and_b32_e32 v237, 0xffff0000, v8
	v_lshlrev_b32_e32 v238, 16, v9
	v_and_b32_e32 v239, 0xffff0000, v9
	v_lshlrev_b32_e32 v240, 16, v10
	v_and_b32_e32 v241, 0xffff0000, v10
	v_lshlrev_b32_e32 v242, 16, v11
	v_and_b32_e32 v243, 0xffff0000, v11
	v_lshlrev_b32_e32 v244, 16, v12
	v_and_b32_e32 v245, 0xffff0000, v12
	v_lshlrev_b32_e32 v246, 16, v13
	v_and_b32_e32 v247, 0xffff0000, v13
	v_lshlrev_b32_e32 v248, 16, v14
	v_and_b32_e32 v249, 0xffff0000, v14
	v_lshlrev_b32_e32 v250, 16, v15
	v_and_b32_e32 v251, 0xffff0000, v15
	v_lshlrev_b32_e32 v140, 16, v41
	v_lshlrev_b32_e32 v141, 16, v44
	v_cndmask_b32_e64 v122, 0, v140, s[52:53]
	v_cndmask_b32_e64 v139, 0, v141, s[54:55]
	v_mov_b32_e32 v123, v236
	v_mov_b32_e32 v138, v251
	v_pk_mov_b32 v[124:125], v[236:237], v[238:239] op_sel:[1,0]
	v_pk_mov_b32 v[126:127], v[238:239], v[240:241] op_sel:[1,0]
	v_pk_mov_b32 v[128:129], v[240:241], v[242:243] op_sel:[1,0]
	v_pk_mov_b32 v[130:131], v[242:243], v[244:245] op_sel:[1,0]
	v_pk_mov_b32 v[132:133], v[244:245], v[246:247] op_sel:[1,0]
	v_pk_mov_b32 v[134:135], v[246:247], v[248:249] op_sel:[1,0]
	v_pk_mov_b32 v[136:137], v[248:249], v[250:251] op_sel:[1,0]
	s_add_u32 s18, s18, 0x2000
	s_addc_u32 s19, s19, 0
	global_load_dwordx4 v[8:11], v60, s[18:19] nt
	global_load_dwordx4 v[12:15], v60, s[18:19] offset:16 nt
	global_load_ushort v41, v61, s[18:19]
	global_load_ushort v44, v62, s[18:19]
	v_pk_mul_f32 v[140:141], v[236:237], s[44:45] op_sel:[0,0] op_sel_hi:[1,0]
	v_pk_fma_f32 v[140:141], v[122:123], s[40:41], v[140:141] op_sel:[0,1,0] op_sel_hi:[1,1,1]
	v_pk_fma_f32 v[140:141], v[124:125], s[46:47], v[140:141] op_sel:[0,1,0] op_sel_hi:[1,1,1]
	v_pk_add_f32 v[140:141], s[50:51], v[140:141] op_sel:[0,0] op_sel_hi:[0,1]
	v_cvt_pk_bf16_f32 v66, v140, v141
	v_pk_mul_f32 v[140:141], v[238:239], s[44:45] op_sel:[0,0] op_sel_hi:[1,0]
	v_pk_fma_f32 v[140:141], v[124:125], s[40:41], v[140:141] op_sel:[0,1,0] op_sel_hi:[1,1,1]
	v_pk_fma_f32 v[140:141], v[126:127], s[46:47], v[140:141] op_sel:[0,1,0] op_sel_hi:[1,1,1]
	v_pk_add_f32 v[140:141], s[50:51], v[140:141] op_sel:[0,0] op_sel_hi:[0,1]
	v_cvt_pk_bf16_f32 v67, v140, v141
	v_pk_mul_f32 v[140:141], v[240:241], s[44:45] op_sel:[0,0] op_sel_hi:[1,0]
	v_pk_fma_f32 v[140:141], v[126:127], s[40:41], v[140:141] op_sel:[0,1,0] op_sel_hi:[1,1,1]
	v_pk_fma_f32 v[140:141], v[128:129], s[46:47], v[140:141] op_sel:[0,1,0] op_sel_hi:[1,1,1]
	v_pk_add_f32 v[140:141], s[50:51], v[140:141] op_sel:[0,0] op_sel_hi:[0,1]
	v_cvt_pk_bf16_f32 v68, v140, v141
	v_pk_mul_f32 v[140:141], v[242:243], s[44:45] op_sel:[0,0] op_sel_hi:[1,0]
	v_pk_fma_f32 v[140:141], v[128:129], s[40:41], v[140:141] op_sel:[0,1,0] op_sel_hi:[1,1,1]
	v_pk_fma_f32 v[140:141], v[130:131], s[46:47], v[140:141] op_sel:[0,1,0] op_sel_hi:[1,1,1]
	v_pk_add_f32 v[140:141], s[50:51], v[140:141] op_sel:[0,0] op_sel_hi:[0,1]
	v_cvt_pk_bf16_f32 v69, v140, v141
	v_pk_mul_f32 v[140:141], v[244:245], s[44:45] op_sel:[0,0] op_sel_hi:[1,0]
	v_pk_fma_f32 v[140:141], v[130:131], s[40:41], v[140:141] op_sel:[0,1,0] op_sel_hi:[1,1,1]
	v_pk_fma_f32 v[140:141], v[132:133], s[46:47], v[140:141] op_sel:[0,1,0] op_sel_hi:[1,1,1]
	v_pk_add_f32 v[140:141], s[50:51], v[140:141] op_sel:[0,0] op_sel_hi:[0,1]
	v_cvt_pk_bf16_f32 v70, v140, v141
	v_pk_mul_f32 v[140:141], v[246:247], s[44:45] op_sel:[0,0] op_sel_hi:[1,0]
	v_pk_fma_f32 v[140:141], v[132:133], s[40:41], v[140:141] op_sel:[0,1,0] op_sel_hi:[1,1,1]
	v_pk_fma_f32 v[140:141], v[134:135], s[46:47], v[140:141] op_sel:[0,1,0] op_sel_hi:[1,1,1]
	v_pk_add_f32 v[140:141], s[50:51], v[140:141] op_sel:[0,0] op_sel_hi:[0,1]
	v_cvt_pk_bf16_f32 v71, v140, v141
	v_pk_mul_f32 v[140:141], v[248:249], s[44:45] op_sel:[0,0] op_sel_hi:[1,0]
	v_pk_fma_f32 v[140:141], v[134:135], s[40:41], v[140:141] op_sel:[0,1,0] op_sel_hi:[1,1,1]
	v_pk_fma_f32 v[140:141], v[136:137], s[46:47], v[140:141] op_sel:[0,1,0] op_sel_hi:[1,1,1]
	v_pk_add_f32 v[140:141], s[50:51], v[140:141] op_sel:[0,0] op_sel_hi:[0,1]
	v_cvt_pk_bf16_f32 v72, v140, v141
	v_pk_mul_f32 v[140:141], v[250:251], s[44:45] op_sel:[0,0] op_sel_hi:[1,0]
	v_pk_fma_f32 v[140:141], v[136:137], s[40:41], v[140:141] op_sel:[0,1,0] op_sel_hi:[1,1,1]
	v_pk_fma_f32 v[140:141], v[138:139], s[46:47], v[140:141] op_sel:[0,1,0] op_sel_hi:[1,1,1]
	v_pk_add_f32 v[140:141], s[50:51], v[140:141] op_sel:[0,0] op_sel_hi:[0,1]
	v_cvt_pk_bf16_f32 v73, v140, v141
	ds_write_b128 v63, v[66:69] offset:36864
	ds_write_b128 v63, v[70:73] offset:36880
	s_waitcnt vmcnt(8)
	v_lshlrev_b32_e32 v236, 16, v32
	v_and_b32_e32 v237, 0xffff0000, v32
	v_lshlrev_b32_e32 v238, 16, v33
	v_and_b32_e32 v239, 0xffff0000, v33
	v_lshlrev_b32_e32 v240, 16, v34
	v_and_b32_e32 v241, 0xffff0000, v34
	v_lshlrev_b32_e32 v242, 16, v35
	v_and_b32_e32 v243, 0xffff0000, v35
	v_lshlrev_b32_e32 v244, 16, v36
	v_and_b32_e32 v245, 0xffff0000, v36
	v_lshlrev_b32_e32 v246, 16, v37
	v_and_b32_e32 v247, 0xffff0000, v37
	v_lshlrev_b32_e32 v248, 16, v38
	v_and_b32_e32 v249, 0xffff0000, v38
	v_lshlrev_b32_e32 v250, 16, v39
	v_and_b32_e32 v251, 0xffff0000, v39
	v_lshlrev_b32_e32 v140, 16, v42
	v_lshlrev_b32_e32 v141, 16, v45
	v_cndmask_b32_e64 v122, 0, v140, s[52:53]
	v_cndmask_b32_e64 v139, 0, v141, s[54:55]
	v_mov_b32_e32 v123, v236
	v_mov_b32_e32 v138, v251
	v_pk_mov_b32 v[124:125], v[236:237], v[238:239] op_sel:[1,0]
	v_pk_mov_b32 v[126:127], v[238:239], v[240:241] op_sel:[1,0]
	v_pk_mov_b32 v[128:129], v[240:241], v[242:243] op_sel:[1,0]
	v_pk_mov_b32 v[130:131], v[242:243], v[244:245] op_sel:[1,0]
	v_pk_mov_b32 v[132:133], v[244:245], v[246:247] op_sel:[1,0]
	v_pk_mov_b32 v[134:135], v[246:247], v[248:249] op_sel:[1,0]
	v_pk_mov_b32 v[136:137], v[248:249], v[250:251] op_sel:[1,0]
	s_add_u32 s20, s20, 0x2000
	s_addc_u32 s21, s21, 0
	global_load_dwordx4 v[32:35], v60, s[20:21] nt
	global_load_dwordx4 v[36:39], v60, s[20:21] offset:16 nt
	global_load_ushort v42, v61, s[20:21]
	global_load_ushort v45, v62, s[20:21]
	v_pk_mul_f32 v[140:141], v[236:237], s[44:45] op_sel:[0,1] op_sel_hi:[1,1]
	v_pk_fma_f32 v[140:141], v[122:123], s[42:43], v[140:141] op_sel:[0,0,0] op_sel_hi:[1,0,1]
	v_pk_fma_f32 v[140:141], v[124:125], s[48:49], v[140:141] op_sel:[0,0,0] op_sel_hi:[1,0,1]
	v_pk_add_f32 v[140:141], s[50:51], v[140:141] op_sel:[1,0] op_sel_hi:[1,1]
	v_cvt_pk_bf16_f32 v66, v140, v141
	v_pk_mul_f32 v[140:141], v[238:239], s[44:45] op_sel:[0,1] op_sel_hi:[1,1]
	v_pk_fma_f32 v[140:141], v[124:125], s[42:43], v[140:141] op_sel:[0,0,0] op_sel_hi:[1,0,1]
	v_pk_fma_f32 v[140:141], v[126:127], s[48:49], v[140:141] op_sel:[0,0,0] op_sel_hi:[1,0,1]
	v_pk_add_f32 v[140:141], s[50:51], v[140:141] op_sel:[1,0] op_sel_hi:[1,1]
	v_cvt_pk_bf16_f32 v67, v140, v141
	v_pk_mul_f32 v[140:141], v[240:241], s[44:45] op_sel:[0,1] op_sel_hi:[1,1]
	v_pk_fma_f32 v[140:141], v[126:127], s[42:43], v[140:141] op_sel:[0,0,0] op_sel_hi:[1,0,1]
	v_pk_fma_f32 v[140:141], v[128:129], s[48:49], v[140:141] op_sel:[0,0,0] op_sel_hi:[1,0,1]
	v_pk_add_f32 v[140:141], s[50:51], v[140:141] op_sel:[1,0] op_sel_hi:[1,1]
	v_cvt_pk_bf16_f32 v68, v140, v141
	v_pk_mul_f32 v[140:141], v[242:243], s[44:45] op_sel:[0,1] op_sel_hi:[1,1]
	v_pk_fma_f32 v[140:141], v[128:129], s[42:43], v[140:141] op_sel:[0,0,0] op_sel_hi:[1,0,1]
	v_pk_fma_f32 v[140:141], v[130:131], s[48:49], v[140:141] op_sel:[0,0,0] op_sel_hi:[1,0,1]
	v_pk_add_f32 v[140:141], s[50:51], v[140:141] op_sel:[1,0] op_sel_hi:[1,1]
	v_cvt_pk_bf16_f32 v69, v140, v141
	v_pk_mul_f32 v[140:141], v[244:245], s[44:45] op_sel:[0,1] op_sel_hi:[1,1]
	v_pk_fma_f32 v[140:141], v[130:131], s[42:43], v[140:141] op_sel:[0,0,0] op_sel_hi:[1,0,1]
	v_pk_fma_f32 v[140:141], v[132:133], s[48:49], v[140:141] op_sel:[0,0,0] op_sel_hi:[1,0,1]
	v_pk_add_f32 v[140:141], s[50:51], v[140:141] op_sel:[1,0] op_sel_hi:[1,1]
	v_cvt_pk_bf16_f32 v70, v140, v141
	v_pk_mul_f32 v[140:141], v[246:247], s[44:45] op_sel:[0,1] op_sel_hi:[1,1]
	v_pk_fma_f32 v[140:141], v[132:133], s[42:43], v[140:141] op_sel:[0,0,0] op_sel_hi:[1,0,1]
	v_pk_fma_f32 v[140:141], v[134:135], s[48:49], v[140:141] op_sel:[0,0,0] op_sel_hi:[1,0,1]
	v_pk_add_f32 v[140:141], s[50:51], v[140:141] op_sel:[1,0] op_sel_hi:[1,1]
	v_cvt_pk_bf16_f32 v71, v140, v141
	v_pk_mul_f32 v[140:141], v[248:249], s[44:45] op_sel:[0,1] op_sel_hi:[1,1]
	v_pk_fma_f32 v[140:141], v[134:135], s[42:43], v[140:141] op_sel:[0,0,0] op_sel_hi:[1,0,1]
	v_pk_fma_f32 v[140:141], v[136:137], s[48:49], v[140:141] op_sel:[0,0,0] op_sel_hi:[1,0,1]
	v_pk_add_f32 v[140:141], s[50:51], v[140:141] op_sel:[1,0] op_sel_hi:[1,1]
	v_cvt_pk_bf16_f32 v72, v140, v141
	v_pk_mul_f32 v[140:141], v[250:251], s[44:45] op_sel:[0,1] op_sel_hi:[1,1]
	v_pk_fma_f32 v[140:141], v[136:137], s[42:43], v[140:141] op_sel:[0,0,0] op_sel_hi:[1,0,1]
	v_pk_fma_f32 v[140:141], v[138:139], s[48:49], v[140:141] op_sel:[0,0,0] op_sel_hi:[1,0,1]
	v_pk_add_f32 v[140:141], s[50:51], v[140:141] op_sel:[1,0] op_sel_hi:[1,1]
	v_cvt_pk_bf16_f32 v73, v140, v141
	ds_write_b128 v55, v[66:69] offset:0
	ds_write_b128 v55, v[70:73] offset:16
	s_waitcnt vmcnt(8)
	v_lshlrev_b32_e32 v236, 16, v0
	v_and_b32_e32 v237, 0xffff0000, v0
	v_lshlrev_b32_e32 v238, 16, v1
	v_and_b32_e32 v239, 0xffff0000, v1
	v_lshlrev_b32_e32 v240, 16, v2
	v_and_b32_e32 v241, 0xffff0000, v2
	v_lshlrev_b32_e32 v242, 16, v3
	v_and_b32_e32 v243, 0xffff0000, v3
	v_lshlrev_b32_e32 v244, 16, v4
	v_and_b32_e32 v245, 0xffff0000, v4
	v_lshlrev_b32_e32 v246, 16, v5
	v_and_b32_e32 v247, 0xffff0000, v5
	v_lshlrev_b32_e32 v248, 16, v6
	v_and_b32_e32 v249, 0xffff0000, v6
	v_lshlrev_b32_e32 v250, 16, v7
	v_and_b32_e32 v251, 0xffff0000, v7
	v_lshlrev_b32_e32 v140, 16, v40
	v_lshlrev_b32_e32 v141, 16, v43
	v_cndmask_b32_e64 v122, 0, v140, s[52:53]
	v_cndmask_b32_e64 v139, 0, v141, s[54:55]
	v_mov_b32_e32 v123, v236
	v_mov_b32_e32 v138, v251
	v_pk_mov_b32 v[124:125], v[236:237], v[238:239] op_sel:[1,0]
	v_pk_mov_b32 v[126:127], v[238:239], v[240:241] op_sel:[1,0]
	v_pk_mov_b32 v[128:129], v[240:241], v[242:243] op_sel:[1,0]
	v_pk_mov_b32 v[130:131], v[242:243], v[244:245] op_sel:[1,0]
	v_pk_mov_b32 v[132:133], v[244:245], v[246:247] op_sel:[1,0]
	v_pk_mov_b32 v[134:135], v[246:247], v[248:249] op_sel:[1,0]
	v_pk_mov_b32 v[136:137], v[248:249], v[250:251] op_sel:[1,0]
	v_pk_mul_f32 v[140:141], v[236:237], s[42:43] op_sel:[0,1] op_sel_hi:[1,1]
	v_pk_fma_f32 v[140:141], v[122:123], s[40:41], v[140:141] op_sel:[0,0,0] op_sel_hi:[1,0,1]
	v_pk_fma_f32 v[140:141], v[124:125], s[46:47], v[140:141] op_sel:[0,0,0] op_sel_hi:[1,0,1]
	v_pk_add_f32 v[140:141], s[48:49], v[140:141] op_sel:[1,0] op_sel_hi:[1,1]
	v_cvt_pk_bf16_f32 v66, v140, v141
	v_pk_mul_f32 v[140:141], v[238:239], s[42:43] op_sel:[0,1] op_sel_hi:[1,1]
	v_pk_fma_f32 v[140:141], v[124:125], s[40:41], v[140:141] op_sel:[0,0,0] op_sel_hi:[1,0,1]
	v_pk_fma_f32 v[140:141], v[126:127], s[46:47], v[140:141] op_sel:[0,0,0] op_sel_hi:[1,0,1]
	v_pk_add_f32 v[140:141], s[48:49], v[140:141] op_sel:[1,0] op_sel_hi:[1,1]
	v_cvt_pk_bf16_f32 v67, v140, v141
	v_pk_mul_f32 v[140:141], v[240:241], s[42:43] op_sel:[0,1] op_sel_hi:[1,1]
	v_pk_fma_f32 v[140:141], v[126:127], s[40:41], v[140:141] op_sel:[0,0,0] op_sel_hi:[1,0,1]
	v_pk_fma_f32 v[140:141], v[128:129], s[46:47], v[140:141] op_sel:[0,0,0] op_sel_hi:[1,0,1]
	v_pk_add_f32 v[140:141], s[48:49], v[140:141] op_sel:[1,0] op_sel_hi:[1,1]
	v_cvt_pk_bf16_f32 v68, v140, v141
	v_pk_mul_f32 v[140:141], v[242:243], s[42:43] op_sel:[0,1] op_sel_hi:[1,1]
	v_pk_fma_f32 v[140:141], v[128:129], s[40:41], v[140:141] op_sel:[0,0,0] op_sel_hi:[1,0,1]
	v_pk_fma_f32 v[140:141], v[130:131], s[46:47], v[140:141] op_sel:[0,0,0] op_sel_hi:[1,0,1]
	v_pk_add_f32 v[140:141], s[48:49], v[140:141] op_sel:[1,0] op_sel_hi:[1,1]
	v_cvt_pk_bf16_f32 v69, v140, v141
	v_pk_mul_f32 v[140:141], v[244:245], s[42:43] op_sel:[0,1] op_sel_hi:[1,1]
	v_pk_fma_f32 v[140:141], v[130:131], s[40:41], v[140:141] op_sel:[0,0,0] op_sel_hi:[1,0,1]
	v_pk_fma_f32 v[140:141], v[132:133], s[46:47], v[140:141] op_sel:[0,0,0] op_sel_hi:[1,0,1]
	v_pk_add_f32 v[140:141], s[48:49], v[140:141] op_sel:[1,0] op_sel_hi:[1,1]
	v_cvt_pk_bf16_f32 v70, v140, v141
	v_pk_mul_f32 v[140:141], v[246:247], s[42:43] op_sel:[0,1] op_sel_hi:[1,1]
	v_pk_fma_f32 v[140:141], v[132:133], s[40:41], v[140:141] op_sel:[0,0,0] op_sel_hi:[1,0,1]
	v_pk_fma_f32 v[140:141], v[134:135], s[46:47], v[140:141] op_sel:[0,0,0] op_sel_hi:[1,0,1]
	v_pk_add_f32 v[140:141], s[48:49], v[140:141] op_sel:[1,0] op_sel_hi:[1,1]
	v_cvt_pk_bf16_f32 v71, v140, v141
	v_pk_mul_f32 v[140:141], v[248:249], s[42:43] op_sel:[0,1] op_sel_hi:[1,1]
	v_pk_fma_f32 v[140:141], v[134:135], s[40:41], v[140:141] op_sel:[0,0,0] op_sel_hi:[1,0,1]
	v_pk_fma_f32 v[140:141], v[136:137], s[46:47], v[140:141] op_sel:[0,0,0] op_sel_hi:[1,0,1]
	v_pk_add_f32 v[140:141], s[48:49], v[140:141] op_sel:[1,0] op_sel_hi:[1,1]
	v_cvt_pk_bf16_f32 v72, v140, v141
	v_pk_mul_f32 v[140:141], v[250:251], s[42:43] op_sel:[0,1] op_sel_hi:[1,1]
	v_pk_fma_f32 v[140:141], v[136:137], s[40:41], v[140:141] op_sel:[0,0,0] op_sel_hi:[1,0,1]
	v_pk_fma_f32 v[140:141], v[138:139], s[46:47], v[140:141] op_sel:[0,0,0] op_sel_hi:[1,0,1]
	v_pk_add_f32 v[140:141], s[48:49], v[140:141] op_sel:[1,0] op_sel_hi:[1,1]
	v_cvt_pk_bf16_f32 v73, v140, v141
	ds_write_b128 v63, v[66:69] offset:28672
	ds_write_b128 v63, v[70:73] offset:28688
	s_waitcnt vmcnt(4)
	v_lshlrev_b32_e32 v236, 16, v8
	v_and_b32_e32 v237, 0xffff0000, v8
	v_lshlrev_b32_e32 v238, 16, v9
	v_and_b32_e32 v239, 0xffff0000, v9
	v_lshlrev_b32_e32 v240, 16, v10
	v_and_b32_e32 v241, 0xffff0000, v10
	v_lshlrev_b32_e32 v242, 16, v11
	v_and_b32_e32 v243, 0xffff0000, v11
	v_lshlrev_b32_e32 v244, 16, v12
	v_and_b32_e32 v245, 0xffff0000, v12
	v_lshlrev_b32_e32 v246, 16, v13
	v_and_b32_e32 v247, 0xffff0000, v13
	v_lshlrev_b32_e32 v248, 16, v14
	v_and_b32_e32 v249, 0xffff0000, v14
	v_lshlrev_b32_e32 v250, 16, v15
	v_and_b32_e32 v251, 0xffff0000, v15
	v_lshlrev_b32_e32 v140, 16, v41
	v_lshlrev_b32_e32 v141, 16, v44
	v_cndmask_b32_e64 v122, 0, v140, s[52:53]
	v_cndmask_b32_e64 v139, 0, v141, s[54:55]
	v_mov_b32_e32 v123, v236
	v_mov_b32_e32 v138, v251
	v_pk_mov_b32 v[124:125], v[236:237], v[238:239] op_sel:[1,0]
	v_pk_mov_b32 v[126:127], v[238:239], v[240:241] op_sel:[1,0]
	v_pk_mov_b32 v[128:129], v[240:241], v[242:243] op_sel:[1,0]
	v_pk_mov_b32 v[130:131], v[242:243], v[244:245] op_sel:[1,0]
	v_pk_mov_b32 v[132:133], v[244:245], v[246:247] op_sel:[1,0]
	v_pk_mov_b32 v[134:135], v[246:247], v[248:249] op_sel:[1,0]
	v_pk_mov_b32 v[136:137], v[248:249], v[250:251] op_sel:[1,0]
	v_pk_mul_f32 v[140:141], v[236:237], s[44:45] op_sel:[0,0] op_sel_hi:[1,0]
	v_pk_fma_f32 v[140:141], v[122:123], s[40:41], v[140:141] op_sel:[0,1,0] op_sel_hi:[1,1,1]
	v_pk_fma_f32 v[140:141], v[124:125], s[46:47], v[140:141] op_sel:[0,1,0] op_sel_hi:[1,1,1]
	v_pk_add_f32 v[140:141], s[50:51], v[140:141] op_sel:[0,0] op_sel_hi:[0,1]
	v_cvt_pk_bf16_f32 v66, v140, v141
	v_pk_mul_f32 v[140:141], v[238:239], s[44:45] op_sel:[0,0] op_sel_hi:[1,0]
	v_pk_fma_f32 v[140:141], v[124:125], s[40:41], v[140:141] op_sel:[0,1,0] op_sel_hi:[1,1,1]
	v_pk_fma_f32 v[140:141], v[126:127], s[46:47], v[140:141] op_sel:[0,1,0] op_sel_hi:[1,1,1]
	v_pk_add_f32 v[140:141], s[50:51], v[140:141] op_sel:[0,0] op_sel_hi:[0,1]
	v_cvt_pk_bf16_f32 v67, v140, v141
	v_pk_mul_f32 v[140:141], v[240:241], s[44:45] op_sel:[0,0] op_sel_hi:[1,0]
	v_pk_fma_f32 v[140:141], v[126:127], s[40:41], v[140:141] op_sel:[0,1,0] op_sel_hi:[1,1,1]
	v_pk_fma_f32 v[140:141], v[128:129], s[46:47], v[140:141] op_sel:[0,1,0] op_sel_hi:[1,1,1]
	v_pk_add_f32 v[140:141], s[50:51], v[140:141] op_sel:[0,0] op_sel_hi:[0,1]
	v_cvt_pk_bf16_f32 v68, v140, v141
	v_pk_mul_f32 v[140:141], v[242:243], s[44:45] op_sel:[0,0] op_sel_hi:[1,0]
	v_pk_fma_f32 v[140:141], v[128:129], s[40:41], v[140:141] op_sel:[0,1,0] op_sel_hi:[1,1,1]
	v_pk_fma_f32 v[140:141], v[130:131], s[46:47], v[140:141] op_sel:[0,1,0] op_sel_hi:[1,1,1]
	v_pk_add_f32 v[140:141], s[50:51], v[140:141] op_sel:[0,0] op_sel_hi:[0,1]
	v_cvt_pk_bf16_f32 v69, v140, v141
	v_pk_mul_f32 v[140:141], v[244:245], s[44:45] op_sel:[0,0] op_sel_hi:[1,0]
	v_pk_fma_f32 v[140:141], v[130:131], s[40:41], v[140:141] op_sel:[0,1,0] op_sel_hi:[1,1,1]
	v_pk_fma_f32 v[140:141], v[132:133], s[46:47], v[140:141] op_sel:[0,1,0] op_sel_hi:[1,1,1]
	v_pk_add_f32 v[140:141], s[50:51], v[140:141] op_sel:[0,0] op_sel_hi:[0,1]
	v_cvt_pk_bf16_f32 v70, v140, v141
	v_pk_mul_f32 v[140:141], v[246:247], s[44:45] op_sel:[0,0] op_sel_hi:[1,0]
	v_pk_fma_f32 v[140:141], v[132:133], s[40:41], v[140:141] op_sel:[0,1,0] op_sel_hi:[1,1,1]
	v_pk_fma_f32 v[140:141], v[134:135], s[46:47], v[140:141] op_sel:[0,1,0] op_sel_hi:[1,1,1]
	v_pk_add_f32 v[140:141], s[50:51], v[140:141] op_sel:[0,0] op_sel_hi:[0,1]
	v_cvt_pk_bf16_f32 v71, v140, v141
	v_pk_mul_f32 v[140:141], v[248:249], s[44:45] op_sel:[0,0] op_sel_hi:[1,0]
	v_pk_fma_f32 v[140:141], v[134:135], s[40:41], v[140:141] op_sel:[0,1,0] op_sel_hi:[1,1,1]
	v_pk_fma_f32 v[140:141], v[136:137], s[46:47], v[140:141] op_sel:[0,1,0] op_sel_hi:[1,1,1]
	v_pk_add_f32 v[140:141], s[50:51], v[140:141] op_sel:[0,0] op_sel_hi:[0,1]
	v_cvt_pk_bf16_f32 v72, v140, v141
	v_pk_mul_f32 v[140:141], v[250:251], s[44:45] op_sel:[0,0] op_sel_hi:[1,0]
	v_pk_fma_f32 v[140:141], v[136:137], s[40:41], v[140:141] op_sel:[0,1,0] op_sel_hi:[1,1,1]
	v_pk_fma_f32 v[140:141], v[138:139], s[46:47], v[140:141] op_sel:[0,1,0] op_sel_hi:[1,1,1]
	v_pk_add_f32 v[140:141], s[50:51], v[140:141] op_sel:[0,0] op_sel_hi:[0,1]
	v_cvt_pk_bf16_f32 v73, v140, v141
	ds_write_b128 v63, v[66:69] offset:45056
	ds_write_b128 v63, v[70:73] offset:45072
	s_waitcnt vmcnt(0)
	v_lshlrev_b32_e32 v236, 16, v32
	v_and_b32_e32 v237, 0xffff0000, v32
	v_lshlrev_b32_e32 v238, 16, v33
	v_and_b32_e32 v239, 0xffff0000, v33
	v_lshlrev_b32_e32 v240, 16, v34
	v_and_b32_e32 v241, 0xffff0000, v34
	v_lshlrev_b32_e32 v242, 16, v35
	v_and_b32_e32 v243, 0xffff0000, v35
	v_lshlrev_b32_e32 v244, 16, v36
	v_and_b32_e32 v245, 0xffff0000, v36
	v_lshlrev_b32_e32 v246, 16, v37
	v_and_b32_e32 v247, 0xffff0000, v37
	v_lshlrev_b32_e32 v248, 16, v38
	v_and_b32_e32 v249, 0xffff0000, v38
	v_lshlrev_b32_e32 v250, 16, v39
	v_and_b32_e32 v251, 0xffff0000, v39
	v_lshlrev_b32_e32 v140, 16, v42
	v_lshlrev_b32_e32 v141, 16, v45
	v_cndmask_b32_e64 v122, 0, v140, s[52:53]
	v_cndmask_b32_e64 v139, 0, v141, s[54:55]
	v_mov_b32_e32 v123, v236
	v_mov_b32_e32 v138, v251
	v_pk_mov_b32 v[124:125], v[236:237], v[238:239] op_sel:[1,0]
	v_pk_mov_b32 v[126:127], v[238:239], v[240:241] op_sel:[1,0]
	v_pk_mov_b32 v[128:129], v[240:241], v[242:243] op_sel:[1,0]
	v_pk_mov_b32 v[130:131], v[242:243], v[244:245] op_sel:[1,0]
	v_pk_mov_b32 v[132:133], v[244:245], v[246:247] op_sel:[1,0]
	v_pk_mov_b32 v[134:135], v[246:247], v[248:249] op_sel:[1,0]
	v_pk_mov_b32 v[136:137], v[248:249], v[250:251] op_sel:[1,0]
	v_pk_mul_f32 v[140:141], v[236:237], s[44:45] op_sel:[0,1] op_sel_hi:[1,1]
	v_pk_fma_f32 v[140:141], v[122:123], s[42:43], v[140:141] op_sel:[0,0,0] op_sel_hi:[1,0,1]
	v_pk_fma_f32 v[140:141], v[124:125], s[48:49], v[140:141] op_sel:[0,0,0] op_sel_hi:[1,0,1]
	v_pk_add_f32 v[140:141], s[50:51], v[140:141] op_sel:[1,0] op_sel_hi:[1,1]
	v_cvt_pk_bf16_f32 v66, v140, v141
	v_pk_mul_f32 v[140:141], v[238:239], s[44:45] op_sel:[0,1] op_sel_hi:[1,1]
	v_pk_fma_f32 v[140:141], v[124:125], s[42:43], v[140:141] op_sel:[0,0,0] op_sel_hi:[1,0,1]
	v_pk_fma_f32 v[140:141], v[126:127], s[48:49], v[140:141] op_sel:[0,0,0] op_sel_hi:[1,0,1]
	v_pk_add_f32 v[140:141], s[50:51], v[140:141] op_sel:[1,0] op_sel_hi:[1,1]
	v_cvt_pk_bf16_f32 v67, v140, v141
	v_pk_mul_f32 v[140:141], v[240:241], s[44:45] op_sel:[0,1] op_sel_hi:[1,1]
	v_pk_fma_f32 v[140:141], v[126:127], s[42:43], v[140:141] op_sel:[0,0,0] op_sel_hi:[1,0,1]
	v_pk_fma_f32 v[140:141], v[128:129], s[48:49], v[140:141] op_sel:[0,0,0] op_sel_hi:[1,0,1]
	v_pk_add_f32 v[140:141], s[50:51], v[140:141] op_sel:[1,0] op_sel_hi:[1,1]
	v_cvt_pk_bf16_f32 v68, v140, v141
	v_pk_mul_f32 v[140:141], v[242:243], s[44:45] op_sel:[0,1] op_sel_hi:[1,1]
	v_pk_fma_f32 v[140:141], v[128:129], s[42:43], v[140:141] op_sel:[0,0,0] op_sel_hi:[1,0,1]
	v_pk_fma_f32 v[140:141], v[130:131], s[48:49], v[140:141] op_sel:[0,0,0] op_sel_hi:[1,0,1]
	v_pk_add_f32 v[140:141], s[50:51], v[140:141] op_sel:[1,0] op_sel_hi:[1,1]
	v_cvt_pk_bf16_f32 v69, v140, v141
	v_pk_mul_f32 v[140:141], v[244:245], s[44:45] op_sel:[0,1] op_sel_hi:[1,1]
	v_pk_fma_f32 v[140:141], v[130:131], s[42:43], v[140:141] op_sel:[0,0,0] op_sel_hi:[1,0,1]
	v_pk_fma_f32 v[140:141], v[132:133], s[48:49], v[140:141] op_sel:[0,0,0] op_sel_hi:[1,0,1]
	v_pk_add_f32 v[140:141], s[50:51], v[140:141] op_sel:[1,0] op_sel_hi:[1,1]
	v_cvt_pk_bf16_f32 v70, v140, v141
	v_pk_mul_f32 v[140:141], v[246:247], s[44:45] op_sel:[0,1] op_sel_hi:[1,1]
	v_pk_fma_f32 v[140:141], v[132:133], s[42:43], v[140:141] op_sel:[0,0,0] op_sel_hi:[1,0,1]
	v_pk_fma_f32 v[140:141], v[134:135], s[48:49], v[140:141] op_sel:[0,0,0] op_sel_hi:[1,0,1]
	v_pk_add_f32 v[140:141], s[50:51], v[140:141] op_sel:[1,0] op_sel_hi:[1,1]
	v_cvt_pk_bf16_f32 v71, v140, v141
	v_pk_mul_f32 v[140:141], v[248:249], s[44:45] op_sel:[0,1] op_sel_hi:[1,1]
	v_pk_fma_f32 v[140:141], v[134:135], s[42:43], v[140:141] op_sel:[0,0,0] op_sel_hi:[1,0,1]
	v_pk_fma_f32 v[140:141], v[136:137], s[48:49], v[140:141] op_sel:[0,0,0] op_sel_hi:[1,0,1]
	v_pk_add_f32 v[140:141], s[50:51], v[140:141] op_sel:[1,0] op_sel_hi:[1,1]
	v_cvt_pk_bf16_f32 v72, v140, v141
	v_pk_mul_f32 v[140:141], v[250:251], s[44:45] op_sel:[0,1] op_sel_hi:[1,1]
	v_pk_fma_f32 v[140:141], v[136:137], s[42:43], v[140:141] op_sel:[0,0,0] op_sel_hi:[1,0,1]
	v_pk_fma_f32 v[140:141], v[138:139], s[48:49], v[140:141] op_sel:[0,0,0] op_sel_hi:[1,0,1]
	v_pk_add_f32 v[140:141], s[50:51], v[140:141] op_sel:[1,0] op_sel_hi:[1,1]
	v_cvt_pk_bf16_f32 v73, v140, v141
	ds_write_b128 v55, v[66:69] offset:10240
	ds_write_b128 v55, v[70:73] offset:10256
	s_branch .Lcv_stage_done
.Lcv_stage_1p:
	s_waitcnt vmcnt(8)
	v_lshlrev_b32_e32 v236, 16, v0
	v_and_b32_e32 v237, 0xffff0000, v0
	v_lshlrev_b32_e32 v238, 16, v1
	v_and_b32_e32 v239, 0xffff0000, v1
	v_lshlrev_b32_e32 v240, 16, v2
	v_and_b32_e32 v241, 0xffff0000, v2
	v_lshlrev_b32_e32 v242, 16, v3
	v_and_b32_e32 v243, 0xffff0000, v3
	v_lshlrev_b32_e32 v244, 16, v4
	v_and_b32_e32 v245, 0xffff0000, v4
	v_lshlrev_b32_e32 v246, 16, v5
	v_and_b32_e32 v247, 0xffff0000, v5
	v_lshlrev_b32_e32 v248, 16, v6
	v_and_b32_e32 v249, 0xffff0000, v6
	v_lshlrev_b32_e32 v250, 16, v7
	v_and_b32_e32 v251, 0xffff0000, v7
	v_lshlrev_b32_e32 v140, 16, v40
	v_lshlrev_b32_e32 v141, 16, v43
	v_cndmask_b32_e64 v122, 0, v140, s[52:53]
	v_cndmask_b32_e64 v139, 0, v141, s[54:55]
	v_mov_b32_e32 v123, v236
	v_mov_b32_e32 v138, v251
	v_pk_mov_b32 v[124:125], v[236:237], v[238:239] op_sel:[1,0]
	v_pk_mov_b32 v[126:127], v[238:239], v[240:241] op_sel:[1,0]
	v_pk_mov_b32 v[128:129], v[240:241], v[242:243] op_sel:[1,0]
	v_pk_mov_b32 v[130:131], v[242:243], v[244:245] op_sel:[1,0]
	v_pk_mov_b32 v[132:133], v[244:245], v[246:247] op_sel:[1,0]
	v_pk_mov_b32 v[134:135], v[246:247], v[248:249] op_sel:[1,0]
	v_pk_mov_b32 v[136:137], v[248:249], v[250:251] op_sel:[1,0]
	v_pk_mul_f32 v[140:141], v[236:237], s[42:43] op_sel:[0,1] op_sel_hi:[1,1]
	v_pk_fma_f32 v[140:141], v[122:123], s[40:41], v[140:141] op_sel:[0,0,0] op_sel_hi:[1,0,1]
	v_pk_fma_f32 v[140:141], v[124:125], s[46:47], v[140:141] op_sel:[0,0,0] op_sel_hi:[1,0,1]
	v_pk_add_f32 v[140:141], s[48:49], v[140:141] op_sel:[1,0] op_sel_hi:[1,1]
	v_cvt_pk_bf16_f32 v66, v140, v141
	v_pk_mul_f32 v[140:141], v[238:239], s[42:43] op_sel:[0,1] op_sel_hi:[1,1]
	v_pk_fma_f32 v[140:141], v[124:125], s[40:41], v[140:141] op_sel:[0,0,0] op_sel_hi:[1,0,1]
	v_pk_fma_f32 v[140:141], v[126:127], s[46:47], v[140:141] op_sel:[0,0,0] op_sel_hi:[1,0,1]
	v_pk_add_f32 v[140:141], s[48:49], v[140:141] op_sel:[1,0] op_sel_hi:[1,1]
	v_cvt_pk_bf16_f32 v67, v140, v141
	v_pk_mul_f32 v[140:141], v[240:241], s[42:43] op_sel:[0,1] op_sel_hi:[1,1]
	v_pk_fma_f32 v[140:141], v[126:127], s[40:41], v[140:141] op_sel:[0,0,0] op_sel_hi:[1,0,1]
	v_pk_fma_f32 v[140:141], v[128:129], s[46:47], v[140:141] op_sel:[0,0,0] op_sel_hi:[1,0,1]
	v_pk_add_f32 v[140:141], s[48:49], v[140:141] op_sel:[1,0] op_sel_hi:[1,1]
	v_cvt_pk_bf16_f32 v68, v140, v141
	v_pk_mul_f32 v[140:141], v[242:243], s[42:43] op_sel:[0,1] op_sel_hi:[1,1]
	v_pk_fma_f32 v[140:141], v[128:129], s[40:41], v[140:141] op_sel:[0,0,0] op_sel_hi:[1,0,1]
	v_pk_fma_f32 v[140:141], v[130:131], s[46:47], v[140:141] op_sel:[0,0,0] op_sel_hi:[1,0,1]
	v_pk_add_f32 v[140:141], s[48:49], v[140:141] op_sel:[1,0] op_sel_hi:[1,1]
	v_cvt_pk_bf16_f32 v69, v140, v141
	v_pk_mul_f32 v[140:141], v[244:245], s[42:43] op_sel:[0,1] op_sel_hi:[1,1]
	v_pk_fma_f32 v[140:141], v[130:131], s[40:41], v[140:141] op_sel:[0,0,0] op_sel_hi:[1,0,1]
	v_pk_fma_f32 v[140:141], v[132:133], s[46:47], v[140:141] op_sel:[0,0,0] op_sel_hi:[1,0,1]
	v_pk_add_f32 v[140:141], s[48:49], v[140:141] op_sel:[1,0] op_sel_hi:[1,1]
	v_cvt_pk_bf16_f32 v70, v140, v141
	v_pk_mul_f32 v[140:141], v[246:247], s[42:43] op_sel:[0,1] op_sel_hi:[1,1]
	v_pk_fma_f32 v[140:141], v[132:133], s[40:41], v[140:141] op_sel:[0,0,0] op_sel_hi:[1,0,1]
	v_pk_fma_f32 v[140:141], v[134:135], s[46:47], v[140:141] op_sel:[0,0,0] op_sel_hi:[1,0,1]
	v_pk_add_f32 v[140:141], s[48:49], v[140:141] op_sel:[1,0] op_sel_hi:[1,1]
	v_cvt_pk_bf16_f32 v71, v140, v141
	v_pk_mul_f32 v[140:141], v[248:249], s[42:43] op_sel:[0,1] op_sel_hi:[1,1]
	v_pk_fma_f32 v[140:141], v[134:135], s[40:41], v[140:141] op_sel:[0,0,0] op_sel_hi:[1,0,1]
	v_pk_fma_f32 v[140:141], v[136:137], s[46:47], v[140:141] op_sel:[0,0,0] op_sel_hi:[1,0,1]
	v_pk_add_f32 v[140:141], s[48:49], v[140:141] op_sel:[1,0] op_sel_hi:[1,1]
	v_cvt_pk_bf16_f32 v72, v140, v141
	v_pk_mul_f32 v[140:141], v[250:251], s[42:43] op_sel:[0,1] op_sel_hi:[1,1]
	v_pk_fma_f32 v[140:141], v[136:137], s[40:41], v[140:141] op_sel:[0,0,0] op_sel_hi:[1,0,1]
	v_pk_fma_f32 v[140:141], v[138:139], s[46:47], v[140:141] op_sel:[0,0,0] op_sel_hi:[1,0,1]
	v_pk_add_f32 v[140:141], s[48:49], v[140:141] op_sel:[1,0] op_sel_hi:[1,1]
	v_cvt_pk_bf16_f32 v73, v140, v141
	ds_write_b128 v63, v[66:69] offset:20480
	ds_write_b128 v63, v[70:73] offset:20496
	s_waitcnt vmcnt(4)
	v_lshlrev_b32_e32 v236, 16, v8
	v_and_b32_e32 v237, 0xffff0000, v8
	v_lshlrev_b32_e32 v238, 16, v9
	v_and_b32_e32 v239, 0xffff0000, v9
	v_lshlrev_b32_e32 v240, 16, v10
	v_and_b32_e32 v241, 0xffff0000, v10
	v_lshlrev_b32_e32 v242, 16, v11
	v_and_b32_e32 v243, 0xffff0000, v11
	v_lshlrev_b32_e32 v244, 16, v12
	v_and_b32_e32 v245, 0xffff0000, v12
	v_lshlrev_b32_e32 v246, 16, v13
	v_and_b32_e32 v247, 0xffff0000, v13
	v_lshlrev_b32_e32 v248, 16, v14
	v_and_b32_e32 v249, 0xffff0000, v14
	v_lshlrev_b32_e32 v250, 16, v15
	v_and_b32_e32 v251, 0xffff0000, v15
	v_lshlrev_b32_e32 v140, 16, v41
	v_lshlrev_b32_e32 v141, 16, v44
	v_cndmask_b32_e64 v122, 0, v140, s[52:53]
	v_cndmask_b32_e64 v139, 0, v141, s[54:55]
	v_mov_b32_e32 v123, v236
	v_mov_b32_e32 v138, v251
	v_pk_mov_b32 v[124:125], v[236:237], v[238:239] op_sel:[1,0]
	v_pk_mov_b32 v[126:127], v[238:239], v[240:241] op_sel:[1,0]
	v_pk_mov_b32 v[128:129], v[240:241], v[242:243] op_sel:[1,0]
	v_pk_mov_b32 v[130:131], v[242:243], v[244:245] op_sel:[1,0]
	v_pk_mov_b32 v[132:133], v[244:245], v[246:247] op_sel:[1,0]
	v_pk_mov_b32 v[134:135], v[246:247], v[248:249] op_sel:[1,0]
	v_pk_mov_b32 v[136:137], v[248:249], v[250:251] op_sel:[1,0]
	v_pk_mul_f32 v[140:141], v[236:237], s[44:45] op_sel:[0,0] op_sel_hi:[1,0]
	v_pk_fma_f32 v[140:141], v[122:123], s[40:41], v[140:141] op_sel:[0,1,0] op_sel_hi:[1,1,1]
	v_pk_fma_f32 v[140:141], v[124:125], s[46:47], v[140:141] op_sel:[0,1,0] op_sel_hi:[1,1,1]
	v_pk_add_f32 v[140:141], s[50:51], v[140:141] op_sel:[0,0] op_sel_hi:[0,1]
	v_cvt_pk_bf16_f32 v66, v140, v141
	v_pk_mul_f32 v[140:141], v[238:239], s[44:45] op_sel:[0,0] op_sel_hi:[1,0]
	v_pk_fma_f32 v[140:141], v[124:125], s[40:41], v[140:141] op_sel:[0,1,0] op_sel_hi:[1,1,1]
	v_pk_fma_f32 v[140:141], v[126:127], s[46:47], v[140:141] op_sel:[0,1,0] op_sel_hi:[1,1,1]
	v_pk_add_f32 v[140:141], s[50:51], v[140:141] op_sel:[0,0] op_sel_hi:[0,1]
	v_cvt_pk_bf16_f32 v67, v140, v141
	v_pk_mul_f32 v[140:141], v[240:241], s[44:45] op_sel:[0,0] op_sel_hi:[1,0]
	v_pk_fma_f32 v[140:141], v[126:127], s[40:41], v[140:141] op_sel:[0,1,0] op_sel_hi:[1,1,1]
	v_pk_fma_f32 v[140:141], v[128:129], s[46:47], v[140:141] op_sel:[0,1,0] op_sel_hi:[1,1,1]
	v_pk_add_f32 v[140:141], s[50:51], v[140:141] op_sel:[0,0] op_sel_hi:[0,1]
	v_cvt_pk_bf16_f32 v68, v140, v141
	v_pk_mul_f32 v[140:141], v[242:243], s[44:45] op_sel:[0,0] op_sel_hi:[1,0]
	v_pk_fma_f32 v[140:141], v[128:129], s[40:41], v[140:141] op_sel:[0,1,0] op_sel_hi:[1,1,1]
	v_pk_fma_f32 v[140:141], v[130:131], s[46:47], v[140:141] op_sel:[0,1,0] op_sel_hi:[1,1,1]
	v_pk_add_f32 v[140:141], s[50:51], v[140:141] op_sel:[0,0] op_sel_hi:[0,1]
	v_cvt_pk_bf16_f32 v69, v140, v141
	v_pk_mul_f32 v[140:141], v[244:245], s[44:45] op_sel:[0,0] op_sel_hi:[1,0]
	v_pk_fma_f32 v[140:141], v[130:131], s[40:41], v[140:141] op_sel:[0,1,0] op_sel_hi:[1,1,1]
	v_pk_fma_f32 v[140:141], v[132:133], s[46:47], v[140:141] op_sel:[0,1,0] op_sel_hi:[1,1,1]
	v_pk_add_f32 v[140:141], s[50:51], v[140:141] op_sel:[0,0] op_sel_hi:[0,1]
	v_cvt_pk_bf16_f32 v70, v140, v141
	v_pk_mul_f32 v[140:141], v[246:247], s[44:45] op_sel:[0,0] op_sel_hi:[1,0]
	v_pk_fma_f32 v[140:141], v[132:133], s[40:41], v[140:141] op_sel:[0,1,0] op_sel_hi:[1,1,1]
	v_pk_fma_f32 v[140:141], v[134:135], s[46:47], v[140:141] op_sel:[0,1,0] op_sel_hi:[1,1,1]
	v_pk_add_f32 v[140:141], s[50:51], v[140:141] op_sel:[0,0] op_sel_hi:[0,1]
	v_cvt_pk_bf16_f32 v71, v140, v141
	v_pk_mul_f32 v[140:141], v[248:249], s[44:45] op_sel:[0,0] op_sel_hi:[1,0]
	v_pk_fma_f32 v[140:141], v[134:135], s[40:41], v[140:141] op_sel:[0,1,0] op_sel_hi:[1,1,1]
	v_pk_fma_f32 v[140:141], v[136:137], s[46:47], v[140:141] op_sel:[0,1,0] op_sel_hi:[1,1,1]
	v_pk_add_f32 v[140:141], s[50:51], v[140:141] op_sel:[0,0] op_sel_hi:[0,1]
	v_cvt_pk_bf16_f32 v72, v140, v141
	v_pk_mul_f32 v[140:141], v[250:251], s[44:45] op_sel:[0,0] op_sel_hi:[1,0]
	v_pk_fma_f32 v[140:141], v[136:137], s[40:41], v[140:141] op_sel:[0,1,0] op_sel_hi:[1,1,1]
	v_pk_fma_f32 v[140:141], v[138:139], s[46:47], v[140:141] op_sel:[0,1,0] op_sel_hi:[1,1,1]
	v_pk_add_f32 v[140:141], s[50:51], v[140:141] op_sel:[0,0] op_sel_hi:[0,1]
	v_cvt_pk_bf16_f32 v73, v140, v141
	ds_write_b128 v63, v[66:69] offset:36864
	ds_write_b128 v63, v[70:73] offset:36880
	s_waitcnt vmcnt(0)
	v_lshlrev_b32_e32 v236, 16, v32
	v_and_b32_e32 v237, 0xffff0000, v32
	v_lshlrev_b32_e32 v238, 16, v33
	v_and_b32_e32 v239, 0xffff0000, v33
	v_lshlrev_b32_e32 v240, 16, v34
	v_and_b32_e32 v241, 0xffff0000, v34
	v_lshlrev_b32_e32 v242, 16, v35
	v_and_b32_e32 v243, 0xffff0000, v35
	v_lshlrev_b32_e32 v244, 16, v36
	v_and_b32_e32 v245, 0xffff0000, v36
	v_lshlrev_b32_e32 v246, 16, v37
	v_and_b32_e32 v247, 0xffff0000, v37
	v_lshlrev_b32_e32 v248, 16, v38
	v_and_b32_e32 v249, 0xffff0000, v38
	v_lshlrev_b32_e32 v250, 16, v39
	v_and_b32_e32 v251, 0xffff0000, v39
	v_lshlrev_b32_e32 v140, 16, v42
	v_lshlrev_b32_e32 v141, 16, v45
	v_cndmask_b32_e64 v122, 0, v140, s[52:53]
	v_cndmask_b32_e64 v139, 0, v141, s[54:55]
	v_mov_b32_e32 v123, v236
	v_mov_b32_e32 v138, v251
	v_pk_mov_b32 v[124:125], v[236:237], v[238:239] op_sel:[1,0]
	v_pk_mov_b32 v[126:127], v[238:239], v[240:241] op_sel:[1,0]
	v_pk_mov_b32 v[128:129], v[240:241], v[242:243] op_sel:[1,0]
	v_pk_mov_b32 v[130:131], v[242:243], v[244:245] op_sel:[1,0]
	v_pk_mov_b32 v[132:133], v[244:245], v[246:247] op_sel:[1,0]
	v_pk_mov_b32 v[134:135], v[246:247], v[248:249] op_sel:[1,0]
	v_pk_mov_b32 v[136:137], v[248:249], v[250:251] op_sel:[1,0]
	v_pk_mul_f32 v[140:141], v[236:237], s[44:45] op_sel:[0,1] op_sel_hi:[1,1]
	v_pk_fma_f32 v[140:141], v[122:123], s[42:43], v[140:141] op_sel:[0,0,0] op_sel_hi:[1,0,1]
	v_pk_fma_f32 v[140:141], v[124:125], s[48:49], v[140:141] op_sel:[0,0,0] op_sel_hi:[1,0,1]
	v_pk_add_f32 v[140:141], s[50:51], v[140:141] op_sel:[1,0] op_sel_hi:[1,1]
	v_cvt_pk_bf16_f32 v66, v140, v141
	v_pk_mul_f32 v[140:141], v[238:239], s[44:45] op_sel:[0,1] op_sel_hi:[1,1]
	v_pk_fma_f32 v[140:141], v[124:125], s[42:43], v[140:141] op_sel:[0,0,0] op_sel_hi:[1,0,1]
	v_pk_fma_f32 v[140:141], v[126:127], s[48:49], v[140:141] op_sel:[0,0,0] op_sel_hi:[1,0,1]
	v_pk_add_f32 v[140:141], s[50:51], v[140:141] op_sel:[1,0] op_sel_hi:[1,1]
	v_cvt_pk_bf16_f32 v67, v140, v141
	v_pk_mul_f32 v[140:141], v[240:241], s[44:45] op_sel:[0,1] op_sel_hi:[1,1]
	v_pk_fma_f32 v[140:141], v[126:127], s[42:43], v[140:141] op_sel:[0,0,0] op_sel_hi:[1,0,1]
	v_pk_fma_f32 v[140:141], v[128:129], s[48:49], v[140:141] op_sel:[0,0,0] op_sel_hi:[1,0,1]
	v_pk_add_f32 v[140:141], s[50:51], v[140:141] op_sel:[1,0] op_sel_hi:[1,1]
	v_cvt_pk_bf16_f32 v68, v140, v141
	v_pk_mul_f32 v[140:141], v[242:243], s[44:45] op_sel:[0,1] op_sel_hi:[1,1]
	v_pk_fma_f32 v[140:141], v[128:129], s[42:43], v[140:141] op_sel:[0,0,0] op_sel_hi:[1,0,1]
	v_pk_fma_f32 v[140:141], v[130:131], s[48:49], v[140:141] op_sel:[0,0,0] op_sel_hi:[1,0,1]
	v_pk_add_f32 v[140:141], s[50:51], v[140:141] op_sel:[1,0] op_sel_hi:[1,1]
	v_cvt_pk_bf16_f32 v69, v140, v141
	v_pk_mul_f32 v[140:141], v[244:245], s[44:45] op_sel:[0,1] op_sel_hi:[1,1]
	v_pk_fma_f32 v[140:141], v[130:131], s[42:43], v[140:141] op_sel:[0,0,0] op_sel_hi:[1,0,1]
	v_pk_fma_f32 v[140:141], v[132:133], s[48:49], v[140:141] op_sel:[0,0,0] op_sel_hi:[1,0,1]
	v_pk_add_f32 v[140:141], s[50:51], v[140:141] op_sel:[1,0] op_sel_hi:[1,1]
	v_cvt_pk_bf16_f32 v70, v140, v141
	v_pk_mul_f32 v[140:141], v[246:247], s[44:45] op_sel:[0,1] op_sel_hi:[1,1]
	v_pk_fma_f32 v[140:141], v[132:133], s[42:43], v[140:141] op_sel:[0,0,0] op_sel_hi:[1,0,1]
	v_pk_fma_f32 v[140:141], v[134:135], s[48:49], v[140:141] op_sel:[0,0,0] op_sel_hi:[1,0,1]
	v_pk_add_f32 v[140:141], s[50:51], v[140:141] op_sel:[1,0] op_sel_hi:[1,1]
	v_cvt_pk_bf16_f32 v71, v140, v141
	v_pk_mul_f32 v[140:141], v[248:249], s[44:45] op_sel:[0,1] op_sel_hi:[1,1]
	v_pk_fma_f32 v[140:141], v[134:135], s[42:43], v[140:141] op_sel:[0,0,0] op_sel_hi:[1,0,1]
	v_pk_fma_f32 v[140:141], v[136:137], s[48:49], v[140:141] op_sel:[0,0,0] op_sel_hi:[1,0,1]
	v_pk_add_f32 v[140:141], s[50:51], v[140:141] op_sel:[1,0] op_sel_hi:[1,1]
	v_cvt_pk_bf16_f32 v72, v140, v141
	v_pk_mul_f32 v[140:141], v[250:251], s[44:45] op_sel:[0,1] op_sel_hi:[1,1]
	v_pk_fma_f32 v[140:141], v[136:137], s[42:43], v[140:141] op_sel:[0,0,0] op_sel_hi:[1,0,1]
	v_pk_fma_f32 v[140:141], v[138:139], s[48:49], v[140:141] op_sel:[0,0,0] op_sel_hi:[1,0,1]
	v_pk_add_f32 v[140:141], s[50:51], v[140:141] op_sel:[1,0] op_sel_hi:[1,1]
	v_cvt_pk_bf16_f32 v73, v140, v141
	ds_write_b128 v55, v[66:69] offset:0
	ds_write_b128 v55, v[70:73] offset:16
.Lcv_stage_done:
	s_mul_hi_i32 s14, s2, 0x6000
	s_branch .LBB0_691
